# MLA: rope half of Q kept in registers for the whole tile loop (four LDS reads fewer per tile and wave); on top of v138
# speedup vs baseline: 1.0146x; 1.0146x over previous
; #define LAS __attribute__((address_space(3)))
; __device__ __forceinline__ int v_st(int k, int c) { const int kk = (k & ~0xC) | ((k & 4) << 1) | ((k & 8) >> 1); return ((kk >> 3) * 4 + (c >> 5)) * 512 + ((kk & 7) * 32 + (c & 31)) * 2; }
; __device__ __forceinline__ int v_rd_base(int lane) { return ((lane & 3) << 3) | (((lane >> 2) & 3) << 6) | (((lane >> 4) & 1) << 5) | (((lane >> 5) & 1) << 8); }
; #define SWRITE1(b) do { *(bf16x8*)(V_lds + (b) * SHM_V + vst0) = vs0; *(bf16x8*)(V_lds + (b) * SHM_V + vst1) = vs1; const int kc = sc * 2; \
;     *(bf16x8*)(K_lds + (b) * SHM_K + KSWZ(sr, kc)) = ks0; *(bf16x8*)(K_lds + (b) * SHM_K + KSWZ(32 + sr, kc)) = ks1; \
;     if constexpr (NQK == 12) *(bf16x8*)(KR_lds + (b) * SHM_KR + KRSWZ(krr, krc)) = kr; } while (0)
; #define SWRITE1(b) do { *(bf16x8*)(V_lds + (b) * SHM_V + vst0) = vs0; *(bf16x8*)(V_lds + (b) * SHM_V + vst1) = vs1; const int kc = sc * 2; \
;     *(bf16x8*)(K_lds + (b) * SHM_K + KSWZ(sr, kc)) = ks0; *(bf16x8*)(K_lds + (b) * SHM_K + KSWZ(32 + sr, kc)) = ks1; \
;     if constexpr (NQK == 12) *(bf16x8*)(KR_lds + (b) * SHM_KR + KRSWZ(krr, krc)) = kr; } while (0)
; template <int NQK, int LDQ, int LDQR> ...
;     ...
;   bf16x8 qr[8]; char* qrl = lds + R_QR + wid * 4096 - 4096;
;   { const bf16_t* Qw = Qb + (long)(wid * 32 + r32) * LDQ + hi * 8;
; #pragma unroll
;     for (int d0 = 0; d0 < 8; ++d0) { qr[d0] = *reinterpret_cast<const bf16x8*>(Qw + d0 * 16); asm volatile("" : "+v"(qr[d0])); }
;     if constexpr (NQK == 12) { const bf16_t* Qw2 = Qrb + (long)(wid * 32 + r32) * LDQR + hi * 8;
; #pragma unroll
;       for (int d0 = 0; d0 < 4; ++d0) *reinterpret_cast<bf16x8*>(qrl + 4096 + KRSWZ(r32, d0 * 2 + hi)) = *reinterpret_cast<const bf16x8*>(Qw2 + d0 * 16); } }
;   const int sr = tid >> 4, sc = (tid & 15) * 8, vst0 = v_st(sr, sc), vst1 = v_st(32 + sr, sc);
;   const int krr = tid >> 3, krc = tid & 7;
;   const int vb0 = (int)(uintptr_t)(LAS char*)V_lds + v_rd_base(lane);
;   bf16x8 vs0, vs1, ks0, ks1, kr;
;     ...
;   f32x16 p0, p1; float mn, al; bf16x8 pa0, pa1, pa2, pa3; const int NT = seq / KVBLK;
;   SLOAD1(0); SWRITE1(0, 0); __syncthreads();
;   if (1 < NT) SLOAD1(KVBLK);
;   int vprev = 2, vcur = 0, vnext = 1;
.LBB0_421:
	s_lshl_b32 s0, s42, 11
	s_and_b32 s8, s46, 7
	s_and_b32 s0, s0, 0x1c00000
	s_lshl_b32 s8, s8, 8
	s_or_b32 s0, s0, s8
	s_lshl_b32 s9, s47, 5
	v_lshl_add_u64 v[168:169], v[158:159], 0, s[0:1]
	v_lshl_add_u64 v[170:171], v[160:161], 0, s[0:1]
	s_lshl_b32 s0, s42, 7
	s_and_b32 s48, s9, 0x3f00
	s_and_b32 s0, s0, 0x1c0000
	s_and_b32 s8, s47, 7
	s_and_b32 s16, s9, 0x3800
	s_lshl_b32 s9, s48, 11
	s_add_u32 s9, s15, s9
	s_addc_u32 s17, s20, 0
	s_lshl_b32 s49, s8, 7
	s_lshl_b32 s18, s8, 8
	s_add_u32 s8, s9, s18
	s_addc_u32 s9, s17, 0
	v_lshl_add_u64 v[0:1], s[8:9], 0, v[148:149]
	v_mov_b32_e32 v167, v151
	v_lshl_add_u64 v[0:1], v[0:1], 0, v[166:167]
	global_load_dwordx4 v[96:99], v[0:1], off
	global_load_dwordx4 v[100:103], v[0:1], off offset:32
	s_lshl_b32 s8, s48, 10
	global_load_dwordx4 v[104:107], v[0:1], off offset:64
	s_add_u32 s8, s21, s8
	global_load_dwordx4 v[108:111], v[0:1], off offset:96
	s_addc_u32 s9, s22, 0
	global_load_dwordx4 v[112:115], v[0:1], off offset:128
	s_add_u32 s8, s8, s49
	global_load_dwordx4 v[116:119], v[0:1], off offset:160
	s_addc_u32 s9, s9, 0
	s_lshl_b32 s19, s16, 11
	global_load_dwordx4 v[120:123], v[0:1], off offset:192
	s_add_u32 s17, s23, s19
	global_load_dwordx4 v[124:127], v[0:1], off offset:224
	v_lshl_add_u64 v[0:1], s[8:9], 0, v[156:157]
	s_addc_u32 s9, s28, 0
	s_add_u32 s8, s17, s18
	s_addc_u32 s9, s9, 0
	s_lshl_b32 s16, s16, 7
	s_add_u32 s16, s29, s16
	s_addc_u32 s17, s30, 0
	s_add_u32 s19, s31, s19
	s_addc_u32 s50, s33, 0
	v_lshl_add_u64 v[12:13], v[0:1], 0, v[166:167]
	s_add_u32 s18, s19, s18
	s_addc_u32 s19, s50, 0
	global_load_dwordx4 v[0:3], v[12:13], off
	global_load_dwordx4 v[4:7], v[12:13], off offset:32
	global_load_dwordx4 v[8:11], v[12:13], off offset:64
	s_nop 0
	global_load_dwordx4 v[12:15], v[12:13], off offset:96
	s_nop 0
	global_load_dwordx4 v[16:19], v207, s[18:19]
	global_load_dwordx4 v[20:23], v208, s[18:19]
	global_load_dwordx4 v[24:27], v207, s[8:9]
	global_load_dwordx4 v[28:31], v208, s[8:9]
	global_load_dwordx4 v[32:35], v209, s[16:17]
	v_add_u32_e32 v36, v176, v177
	v_add_u32_e32 v37, v176, v178
	v_add_u32_e32 v38, v176, v179
	v_add_u32_e32 v39, v176, v180
	v_add_u32_e32 v40, 0, v181
	v_add_u32_e32 v41, 0, v182
	v_add_u32_e32 v42, 0, v184
	v_add_u32_e32 v43, 0, v185
	v_lshl_add_u64 v[172:173], v[162:163], 0, s[0:1]
	v_mov_b32_e32 v165, 0xf149f2ca
	s_mov_b32 s0, 0
	s_mov_b32 s50, 0
	v_mov_b32_e32 v167, 0
	s_waitcnt vmcnt(8)
	ds_write_b128 v36, v[0:3]
	s_waitcnt vmcnt(7)
	ds_write_b128 v37, v[4:7]
	s_waitcnt vmcnt(6)
	ds_write_b128 v38, v[8:11]
	s_waitcnt vmcnt(5)
	ds_write_b128 v39, v[12:15]
	s_waitcnt vmcnt(4)
	ds_write_b128 v40, v[16:19]
	s_waitcnt vmcnt(3)
	ds_write_b128 v41, v[20:23]
	s_waitcnt vmcnt(2)
	ds_write_b128 v42, v[24:27] offset:49152
	s_waitcnt vmcnt(1)
	ds_write_b128 v43, v[28:31] offset:49152
	s_waitcnt vmcnt(0)
	ds_write_b128 v186, v[32:35]
	s_waitcnt lgkmcnt(0)
	s_barrier
	global_load_dwordx4 v[140:143], v210, s[16:17]
	global_load_dwordx4 v[144:147], v211, s[8:9]
	global_load_dwordx4 v[136:139], v212, s[8:9]
	global_load_dwordx4 v[132:135], v211, s[18:19]
	global_load_dwordx4 v[128:131], v212, s[18:19]
	v_mov_b32_e32 v14, v151
	v_mov_b32_e32 v15, v151
	v_mov_b32_e32 v0, v151
	v_mov_b32_e32 v1, v151
	v_mov_b32_e32 v2, v151
	v_mov_b32_e32 v3, v151
	v_mov_b32_e32 v4, v151
	v_mov_b32_e32 v5, v151
	v_mov_b32_e32 v6, v151
	v_mov_b32_e32 v7, v151
	v_mov_b32_e32 v8, v151
	v_mov_b32_e32 v9, v151
	v_mov_b32_e32 v10, v151
	v_mov_b32_e32 v11, v151
	v_mov_b32_e32 v12, v151
	v_mov_b32_e32 v13, v151
	v_mov_b64_e32 v[30:31], v[14:15]
	v_mov_b64_e32 v[46:47], v[14:15]
	v_mov_b64_e32 v[62:63], v[14:15]
	s_mov_b64 s[16:17], 0
	v_mov_b64_e32 v[28:29], v[12:13]
	v_mov_b64_e32 v[26:27], v[10:11]
	v_mov_b64_e32 v[24:25], v[8:9]
	v_mov_b64_e32 v[22:23], v[6:7]
	v_mov_b64_e32 v[20:21], v[4:5]
	v_mov_b64_e32 v[18:19], v[2:3]
	v_mov_b64_e32 v[16:17], v[0:1]
	v_mov_b64_e32 v[44:45], v[12:13]
	v_mov_b64_e32 v[42:43], v[10:11]
	v_mov_b64_e32 v[40:41], v[8:9]
	v_mov_b64_e32 v[38:39], v[6:7]
	v_mov_b64_e32 v[36:37], v[4:5]
	v_mov_b64_e32 v[34:35], v[2:3]
	v_mov_b64_e32 v[32:33], v[0:1]
	v_mov_b64_e32 v[60:61], v[12:13]
	v_mov_b64_e32 v[58:59], v[10:11]
	v_mov_b64_e32 v[56:57], v[8:9]
	v_mov_b64_e32 v[54:55], v[6:7]
	v_mov_b64_e32 v[52:53], v[4:5]
	v_mov_b64_e32 v[50:51], v[2:3]
	v_mov_b64_e32 v[48:49], v[0:1]
	s_mov_b32 s8, 1
	s_mov_b32 s18, 2
	v_add_u32_e32 v213, v175, v200
	ds_read_b128 v[240:243], v213
	v_add_u32_e32 v213, v175, v201
	ds_read_b128 v[244:247], v213
	v_add_u32_e32 v213, v175, v202
	ds_read_b128 v[248:251], v213
	v_add_u32_e32 v213, v175, v203
	ds_read_b128 v[252:255], v213
	s_waitcnt lgkmcnt(0)

; __device__ __forceinline__ void partialSM(f32x16& p0, f32x16& p1, float& m_reg, float& mn, float& alpha, const float C, const float thr_raw) {
;   float pmax = p0[0];
; #pragma unroll
;   for (int r = 1; r < 16; ++r) pmax = fmaxf(pmax, p0[r]);
; #pragma unroll
;   for (int r = 0; r < 16; ++r) pmax = fmaxf(pmax, p1[r]);
;   { auto rr = __builtin_amdgcn_permlane32_swap(__float_as_uint(pmax), __float_as_uint(pmax), false, false);
;     pmax = fmaxf(__uint_as_float(rr[0]), __uint_as_float(rr[1])); }
;   if (__builtin_expect(__all(pmax - m_reg <= thr_raw), 1)) { mn = m_reg; alpha = 1.f; }
;   else { mn = fmaxf(m_reg, pmax); alpha = __builtin_amdgcn_exp2f((m_reg - mn) * C); m_reg = mn; }
;   const float mnC = -mn * C;
; template <int NQK, int NREG>
; __device__ __forceinline__ void qkt(f32x16& p0, f32x16& p1, const char* Ks, const char* KRs, const bf16x8* qr, const char* qrl, int r32, int hi) {
;   p0 = f32x16{}; p1 = f32x16{};
; #pragma unroll
;   for (int d0 = 0; d0 < 8; ++d0) { const int cb = (d0 * 16 + hi * 8) * 2;
;     bf16x8 b0 = *reinterpret_cast<const bf16x8*>(Ks + KSWZ(r32, cb));
;     bf16x8 b1 = *reinterpret_cast<const bf16x8*>(Ks + KSWZ(32 + r32, cb));
;     bf16x8 qq; if (d0 < NREG) qq = qr[d0 < NREG ? d0 : 0]; else qq = *reinterpret_cast<const bf16x8*>(qrl + KRSWZ(r32, (d0 - 4) * 2 + hi));
;     p0 = __builtin_amdgcn_mfma_f32_32x32x16_bf16(b0, qq, p0, 0, 0, 0);
;     p1 = __builtin_amdgcn_mfma_f32_32x32x16_bf16(b1, qq, p1, 0, 0, 0); }
;   if constexpr (NQK == 12) {
; #pragma unroll
;     for (int d0 = 0; d0 < 4; ++d0) { const int ch = d0 * 2 + hi;
;       bf16x8 b0 = *reinterpret_cast<const bf16x8*>(KRs + KRSWZ(r32, ch));
;       bf16x8 b1 = *reinterpret_cast<const bf16x8*>(KRs + KRSWZ(32 + r32, ch));
;       const bf16x8 qq = *reinterpret_cast<const bf16x8*>(qrl + 4096 + KRSWZ(r32, ch));
;       p0 = __builtin_amdgcn_mfma_f32_32x32x16_bf16(b0, qq, p0, 0, 0, 0);
;       p1 = __builtin_amdgcn_mfma_f32_32x32x16_bf16(b1, qq, p1, 0, 0, 0); }
;   }
; }
.LBB0_424:
	s_or_b64 exec, exec, s[8:9]
	s_and_b32 s52, s0, 1
	s_lshl_b32 s8, s52, 14
	s_lshl_b32 s9, s52, 13
	s_add_i32 s9, s9, 0x14000
	v_add3_u32 v213, s8, v189, v155
	ds_read_b128 v[214:217], v213 offset:49152
	ds_read_b128 v[218:221], v213 offset:57344
	v_add3_u32 v213, s8, v190, v155
	ds_read_b128 v[222:225], v213 offset:49152
	ds_read_b128 v[226:229], v213 offset:57344
	v_add3_u32 v213, s8, v191, v155
	ds_read_b128 v[232:235], v213 offset:49152
	ds_read_b128 v[236:239], v213 offset:57344
	s_waitcnt lgkmcnt(4)
	v_mfma_f32_32x32x16_bf16 v[80:95], v[214:217], v[96:99], 0
	v_mfma_f32_32x32x16_bf16 v[64:79], v[218:221], v[96:99], 0
	v_add3_u32 v213, s8, v195, v155
	ds_read_b128 v[214:217], v213 offset:49152
	ds_read_b128 v[218:221], v213 offset:57344
	s_waitcnt lgkmcnt(4)
	v_mfma_f32_32x32x16_bf16 v[80:95], v[222:225], v[100:103], v[80:95]
	v_mfma_f32_32x32x16_bf16 v[64:79], v[226:229], v[100:103], v[64:79]
	v_add3_u32 v213, s8, v196, v155
	ds_read_b128 v[222:225], v213 offset:49152
	ds_read_b128 v[226:229], v213 offset:57344
	s_waitcnt lgkmcnt(4)
	v_mfma_f32_32x32x16_bf16 v[80:95], v[232:235], v[104:107], v[80:95]
	v_mfma_f32_32x32x16_bf16 v[64:79], v[236:239], v[104:107], v[64:79]
	v_add3_u32 v213, s8, v197, v155
	ds_read_b128 v[232:235], v213 offset:49152
	ds_read_b128 v[236:239], v213 offset:57344
	s_waitcnt lgkmcnt(4)
	v_mfma_f32_32x32x16_bf16 v[80:95], v[214:217], v[108:111], v[80:95]
	v_mfma_f32_32x32x16_bf16 v[64:79], v[218:221], v[108:111], v[64:79]
	v_add3_u32 v213, s8, v198, v155
	ds_read_b128 v[214:217], v213 offset:49152
	ds_read_b128 v[218:221], v213 offset:57344
	s_waitcnt lgkmcnt(4)
	v_mfma_f32_32x32x16_bf16 v[80:95], v[222:225], v[112:115], v[80:95]
	v_mfma_f32_32x32x16_bf16 v[64:79], v[226:229], v[112:115], v[64:79]
	v_add3_u32 v213, s8, v199, v155
	ds_read_b128 v[222:225], v213 offset:49152
	ds_read_b128 v[226:229], v213 offset:57344
	s_waitcnt lgkmcnt(4)
	v_mfma_f32_32x32x16_bf16 v[80:95], v[232:235], v[116:119], v[80:95]
	v_mfma_f32_32x32x16_bf16 v[64:79], v[236:239], v[116:119], v[64:79]
	v_add_u32_e32 v213, s9, v200
	ds_read_b128 v[232:235], v213
	ds_read_b128 v[236:239], v213 offset:4096
	s_waitcnt lgkmcnt(4)
	v_mfma_f32_32x32x16_bf16 v[80:95], v[214:217], v[120:123], v[80:95]
	v_mfma_f32_32x32x16_bf16 v[64:79], v[218:221], v[120:123], v[64:79]
	v_add_u32_e32 v213, s9, v201
	ds_read_b128 v[214:217], v213
	ds_read_b128 v[218:221], v213 offset:4096
	s_waitcnt lgkmcnt(4)
	v_mfma_f32_32x32x16_bf16 v[80:95], v[222:225], v[124:127], v[80:95]
	v_mfma_f32_32x32x16_bf16 v[64:79], v[226:229], v[124:127], v[64:79]
	v_add_u32_e32 v213, s9, v202
	ds_read_b128 v[222:225], v213
	ds_read_b128 v[226:229], v213 offset:4096
	s_waitcnt lgkmcnt(4)
	v_mfma_f32_32x32x16_bf16 v[80:95], v[232:235], v[240:243], v[80:95]
	v_mfma_f32_32x32x16_bf16 v[64:79], v[236:239], v[240:243], v[64:79]
	v_add_u32_e32 v213, s9, v203
	ds_read_b128 v[232:235], v213
	ds_read_b128 v[236:239], v213 offset:4096
	s_waitcnt lgkmcnt(4)
	v_mfma_f32_32x32x16_bf16 v[80:95], v[214:217], v[244:247], v[80:95]
	v_mfma_f32_32x32x16_bf16 v[64:79], v[218:221], v[244:247], v[64:79]
	s_waitcnt lgkmcnt(2)
	v_mfma_f32_32x32x16_bf16 v[80:95], v[222:225], v[248:251], v[80:95]
	v_mfma_f32_32x32x16_bf16 v[64:79], v[226:229], v[248:251], v[64:79]
	s_waitcnt lgkmcnt(0)
	v_mfma_f32_32x32x16_bf16 v[80:95], v[232:235], v[252:255], v[80:95]
	v_mfma_f32_32x32x16_bf16 v[64:79], v[236:239], v[252:255], v[64:79]
	s_setprio 0
	s_nop 10
	v_max_f32_e32 v213, v81, v81
	v_max_f32_e32 v230, v80, v80
	v_max_f32_e32 v213, v230, v213
	v_max3_f32 v213, v213, v82, v83
	v_max3_f32 v213, v213, v84, v85
	v_max3_f32 v213, v213, v86, v87
	v_max3_f32 v213, v213, v88, v89
	v_max3_f32 v213, v213, v90, v91
	v_max3_f32 v213, v213, v92, v93
	v_max3_f32 v213, v213, v94, v95
	v_max3_f32 v213, v213, v64, v65
	v_max3_f32 v213, v213, v66, v67
	v_max3_f32 v213, v213, v68, v69
	v_max3_f32 v213, v213, v70, v71
	v_max3_f32 v213, v213, v72, v73
	v_max3_f32 v213, v213, v74, v75
	v_max3_f32 v213, v213, v76, v77
	v_max3_f32 v213, v213, v78, v79
	v_mov_b32_e32 v214, v213
	s_nop 1
	v_permlane32_swap_b32_e32 v213, v214
	v_max_f32_e32 v214, v214, v214
	v_max_f32_e32 v213, v213, v213
	v_max_f32_e32 v213, v213, v214
	v_max_f32_e32 v214, v165, v165
	v_max_f32_e32 v214, v214, v213
	v_sub_f32_e32 v215, v213, v165
	v_sub_f32_e32 v213, v165, v214
	v_mul_f32_e32 v213, 0x3dd53b94, v213
	v_exp_f32_e32 v213, v213
	v_cmp_ge_f32_e32 vcc, s44, v215
	s_cmp_eq_u64 vcc, exec
	s_cselect_b64 s[8:9], -1, 0
	v_cndmask_b32_e64 v213, v213, 1.0, s[8:9]
	v_cmp_gt_f32_e32 vcc, 1.0, v213
	s_cbranch_vccz .LBB0_428
	s_and_saveexec_b64 s[18:19], s[4:5]
	ds_write_b32 v194, v213 offset:128
	s_or_b64 exec, exec, s[18:19]
	s_waitcnt lgkmcnt(0)
	v_add_u32_e32 v215, v174, v188
	ds_read_b128 v[216:219], v215 offset:224
	ds_read_b128 v[220:223], v215 offset:192
	ds_read_b128 v[224:227], v215 offset:160
	ds_read_b128 v[228:231], v215 offset:128
	s_waitcnt lgkmcnt(3)
	v_pk_mul_f32 v[12:13], v[12:13], v[216:217]
	s_waitcnt lgkmcnt(2)
	v_pk_mul_f32 v[8:9], v[8:9], v[220:221]
	s_waitcnt lgkmcnt(1)
	v_pk_mul_f32 v[4:5], v[4:5], v[224:225]
	v_pk_mul_f32 v[14:15], v[14:15], v[218:219]
	v_pk_mul_f32 v[10:11], v[10:11], v[222:223]
	v_pk_mul_f32 v[6:7], v[6:7], v[226:227]
	s_waitcnt lgkmcnt(0)
	v_pk_mul_f32 v[2:3], v[2:3], v[230:231]
	v_pk_mul_f32 v[0:1], v[0:1], v[228:229]
	v_pk_mul_f32 v[28:29], v[28:29], v[216:217]
	v_pk_mul_f32 v[24:25], v[24:25], v[220:221]
	v_pk_mul_f32 v[20:21], v[20:21], v[224:225]
	v_pk_mul_f32 v[30:31], v[30:31], v[218:219]
	v_pk_mul_f32 v[26:27], v[26:27], v[222:223]
	v_pk_mul_f32 v[22:23], v[22:23], v[226:227]
	v_pk_mul_f32 v[18:19], v[18:19], v[230:231]
	v_pk_mul_f32 v[16:17], v[16:17], v[228:229]
	v_pk_mul_f32 v[44:45], v[44:45], v[216:217]
	v_pk_mul_f32 v[40:41], v[40:41], v[220:221]
	v_pk_mul_f32 v[36:37], v[36:37], v[224:225]
	v_pk_mul_f32 v[46:47], v[46:47], v[218:219]
	v_pk_mul_f32 v[42:43], v[42:43], v[222:223]
	v_pk_mul_f32 v[38:39], v[38:39], v[226:227]
	v_pk_mul_f32 v[34:35], v[34:35], v[230:231]
	v_pk_mul_f32 v[32:33], v[32:33], v[228:229]
	v_pk_mul_f32 v[60:61], v[60:61], v[216:217]
	v_pk_mul_f32 v[56:57], v[56:57], v[220:221]
	v_pk_mul_f32 v[52:53], v[52:53], v[224:225]
	v_pk_mul_f32 v[62:63], v[62:63], v[218:219]
	v_pk_mul_f32 v[58:59], v[58:59], v[222:223]
	v_pk_mul_f32 v[54:55], v[54:55], v[226:227]
	v_pk_mul_f32 v[50:51], v[50:51], v[230:231]
	v_pk_mul_f32 v[48:49], v[48:49], v[228:229]
